# P5 sliding-window and dilated items: hand-written band attention loop (all K/V tiles prefetched per item, lean softmax); registers saved/restored via LDS
# speedup vs baseline: 1.0121x; 1.0121x over previous
.LBB0_716:
	v_readlane_b32 s1, v254, 0
	s_branch .Lband_entry
.Lband_exit:
.LBB0_718:
	s_mov_b64 s[2:3], s[70:71]
	s_getreg_b32 s4, hwreg(HW_REG_XCC_ID, 0, 4)
	s_waitcnt vmcnt(0)
	s_barrier
	s_mov_b64 s[0:1], exec
	v_readlane_b32 s6, v254, 2
	v_readlane_b32 s7, v254, 3
	s_and_b64 s[6:7], s[0:1], s[6:7]
	s_mov_b64 exec, s[6:7]
	s_cbranch_execz .LBB0_1181
	v_readlane_b32 s5, v254, 63
	s_load_dwordx2 s[2:3], s[2:3], 0x98
	s_waitcnt vmcnt(0) expcnt(0) lgkmcnt(0)
	v_mov_b32_e32 v0, s5
	ds_read_b32 v3, v0
	v_readlane_b32 s5, v255, 0
	s_and_b32 s46, s4, 15
	s_waitcnt lgkmcnt(0)
	v_cmp_ne_u32_e32 vcc, 0, v3
	v_mov_b32_e32 v0, s5
	ds_read_b32 v2, v0
	s_cbranch_vccnz .LBB0_1145
	s_add_u32 s4, s2, 0x1df80200
	s_addc_u32 s5, s3, 0
	s_add_u32 s6, s2, 0x1df80400
	s_addc_u32 s7, s3, 0
	s_add_u32 s8, s2, 0x1df80500
	s_addc_u32 s9, s3, 0
	s_add_u32 s10, s2, 0x1df80600
	s_addc_u32 s11, s3, 0
	s_add_u32 s12, s2, 0x1df80700
	s_addc_u32 s13, s3, 0
	s_add_u32 s14, s2, 0x1df80800
	s_addc_u32 s15, s3, 0
	s_add_u32 s16, s2, 0x1df80900
	s_addc_u32 s17, s3, 0
	s_add_u32 s18, s2, 0x1df80a00
	s_addc_u32 s19, s3, 0
	s_add_u32 s20, s2, 0x1df80b00
	s_addc_u32 s21, s3, 0
	s_add_u32 s22, s2, 0x1df80c00
	s_addc_u32 s23, s3, 0
	s_add_u32 s24, s2, 0x1df80d00
	s_addc_u32 s25, s3, 0
	s_add_u32 s26, s2, 0x1df80e00
	s_addc_u32 s27, s3, 0
	s_add_u32 s28, s2, 0x1df80f00
	s_addc_u32 s29, s3, 0
	s_add_u32 s30, s2, 0x1df81000
	s_addc_u32 s31, s3, 0
	s_add_u32 s34, s2, 0x1df81100
	s_addc_u32 s35, s3, 0
	s_add_u32 s36, s2, 0x1df81200
	s_addc_u32 s37, s3, 0
	s_add_u32 s38, s2, 0x1df81300
	s_addc_u32 s39, s3, 0
	s_mov_b32 s47, 1
	s_branch .LBB0_1133
.Lband_entry:
	s_waitcnt vmcnt(0)
	v_lshlrev_b32_e32 v183, 2, v220
	v_add_u32_e32 v2, 0x10000, v183
	ds_write_b32 v183, v162 offset:0
	ds_write_b32 v183, v163 offset:2048
	ds_write_b32 v183, v164 offset:4096
	ds_write_b32 v183, v165 offset:6144
	ds_write_b32 v183, v166 offset:8192
	ds_write_b32 v183, v167 offset:10240
	ds_write_b32 v183, v168 offset:12288
	ds_write_b32 v183, v169 offset:14336
	ds_write_b32 v183, v170 offset:16384
	ds_write_b32 v183, v174 offset:18432
	ds_write_b32 v183, v175 offset:20480
	ds_write_b32 v183, v176 offset:22528
	ds_write_b32 v183, v177 offset:24576
	ds_write_b32 v183, v216 offset:26624
	ds_write_b32 v183, v217 offset:28672
	ds_write_b32 v183, v218 offset:30720
	ds_write_b32 v183, v219 offset:32768
	ds_write_b32 v183, v225 offset:34816
	ds_write_b32 v183, v227 offset:36864
	ds_write_b32 v183, v236 offset:38912
	ds_write_b32 v183, v237 offset:40960
	ds_write_b32 v183, v249 offset:43008
	ds_write_b32 v183, v200 offset:45056
	ds_write_b32 v183, v201 offset:47104
	ds_write_b32 v183, v202 offset:49152
	ds_write_b32 v183, v203 offset:51200
	ds_write_b32 v183, v204 offset:53248
	ds_write_b32 v183, v205 offset:55296
	ds_write_b32 v183, v206 offset:57344
	ds_write_b32 v183, v207 offset:59392
	ds_write_b32 v183, v208 offset:61440
	ds_write_b32 v183, v209 offset:63488
	ds_write_b32 v2, v210 offset:0
	ds_write_b32 v2, v211 offset:2048
	ds_write_b32 v2, v212 offset:4096
	ds_write_b32 v2, v213 offset:6144
	ds_write_b32 v2, v214 offset:8192
	ds_write_b32 v2, v215 offset:10240
	v_lshrrev_b32_e32 v183, 6, v220
	v_lshlrev_b32_e32 v183, 7, v183
	v_add_u32_e32 v183, 0x13000, v183
	v_mov_b32_e32 v3, s2
	ds_write_b32 v183, v3 offset:0
	v_mov_b32_e32 v3, s3
	ds_write_b32 v183, v3 offset:4
	v_mov_b32_e32 v3, s4
	ds_write_b32 v183, v3 offset:8
	v_mov_b32_e32 v3, s5
	ds_write_b32 v183, v3 offset:12
	v_mov_b32_e32 v3, s6
	ds_write_b32 v183, v3 offset:16
	v_mov_b32_e32 v3, s7
	ds_write_b32 v183, v3 offset:20
	v_mov_b32_e32 v3, s8
	ds_write_b32 v183, v3 offset:24
	v_mov_b32_e32 v3, s9
	ds_write_b32 v183, v3 offset:28
	v_mov_b32_e32 v3, s10
	ds_write_b32 v183, v3 offset:32
	v_mov_b32_e32 v3, s11
	ds_write_b32 v183, v3 offset:36
	v_mov_b32_e32 v3, s12
	ds_write_b32 v183, v3 offset:40
	v_mov_b32_e32 v3, s13
	ds_write_b32 v183, v3 offset:44
	v_mov_b32_e32 v3, s14
	ds_write_b32 v183, v3 offset:48
	v_mov_b32_e32 v3, s15
	ds_write_b32 v183, v3 offset:52
	v_mov_b32_e32 v3, s16
	ds_write_b32 v183, v3 offset:56
	v_mov_b32_e32 v3, s17
	ds_write_b32 v183, v3 offset:60
	v_mov_b32_e32 v3, s18
	ds_write_b32 v183, v3 offset:64
	v_mov_b32_e32 v3, s19
	ds_write_b32 v183, v3 offset:68
	v_mov_b32_e32 v3, s20
	ds_write_b32 v183, v3 offset:72
	v_mov_b32_e32 v3, s21
	ds_write_b32 v183, v3 offset:76
	v_mov_b32_e32 v3, s22
	ds_write_b32 v183, v3 offset:80
	v_mov_b32_e32 v3, s23
	ds_write_b32 v183, v3 offset:84
	v_mov_b32_e32 v3, s24
	ds_write_b32 v183, v3 offset:88
	v_mov_b32_e32 v3, s25
	ds_write_b32 v183, v3 offset:92
	v_mov_b32_e32 v3, s26
	ds_write_b32 v183, v3 offset:96
	v_mov_b32_e32 v3, s27
	ds_write_b32 v183, v3 offset:100
	v_mov_b32_e32 v3, s28
	ds_write_b32 v183, v3 offset:104
	v_mov_b32_e32 v3, s29
	ds_write_b32 v183, v3 offset:108
	v_mov_b32_e32 v3, s30
	ds_write_b32 v183, v3 offset:112
	s_load_dwordx2 s[18:19], s[70:71], 0x98
	s_load_dwordx2 s[20:21], s[70:71], 0x58
	v_and_b32_e32 v163, 31, v173
	v_lshrrev_b32_e32 v164, 5, v173
	v_lshlrev_b32_e32 v162, 4, v173
	v_mov_b32_e32 v227, 0xff800000
	v_lshlrev_b32_e32 v183, 2, v164
	v_sub_u32_e32 v170, v163, v183
	v_xor_b32_e32 v249, 32, v173
	v_lshlrev_b32_e32 v249, 2, v249
	s_mov_b32 s0, s1
	s_waitcnt lgkmcnt(0)
.Lband_item:
	s_cmp_lt_u32 s0, 0x1000
	s_cbranch_scc0 .Lband_dec_dil
	s_and_b32 s8, s0, 0x7f
	s_lshr_b32 s29, s0, 7
	s_lshr_b32 s23, s29, 2
	s_and_b32 s22, s29, 3
	s_lshr_b32 s16, s22, 1
	s_mov_b32 s9, 0
	s_mov_b32 s10, 0
	s_mov_b32 s15, 1
	s_mov_b32 s1, 0
	s_mov_b32 s14, 11
	s_lshl_b32 s13, s22, 7
	s_add_i32 s13, s13, 0xb00
	s_lshl_b32 s12, s16, 7
	s_add_i32 s12, s12, 0xd00
	s_lshl_b32 s17, s23, 1
	s_add_i32 s17, s17, s16
	s_lshl_b32 s17, s17, 19
	s_add_u32 s4, s18, s17
	s_addc_u32 s5, s19, 0
	s_add_u32 s4, s4, 0x1f800000
	s_addc_u32 s5, s5, 0
	s_lshl_b32 s17, s23, 23
	s_add_i32 s16, s22, 8
	s_lshl_b32 s16, s16, 7
	s_add_i32 s17, s17, s16
	s_add_u32 s6, s18, s17
	s_addc_u32 s7, s19, 0
	s_add_u32 s6, s6, 0x14600000
	s_addc_u32 s7, s7, 0
	s_add_i32 s24, s22, 1
	v_readlane_b32 s16, v255, 29
	s_nop 0
	s_add_i32 s16, s16, s22
	s_lshl_b32 s16, s16, 2
	s_load_dword s30, s[20:21], s16
	s_branch .Lband_dec_done
.Lband_dec_dil:
	s_sub_i32 s17, s0, 0x1000
	s_and_b32 s16, s17, 0x7f
	s_lshr_b32 s29, s17, 7
	s_and_b32 s29, s29, 31
	s_lshr_b32 s24, s17, 12
	s_lshr_b32 s23, s29, 2
	s_and_b32 s22, s29, 3
	s_lshl_b32 s9, s24, 1
	s_lshl_b32 s16, s16, 5
	s_sub_i32 s17, 12, s9
	s_lshr_b32 s10, s16, s17
	s_lshr_b32 s17, 0x1000, s9
	s_add_i32 s17, s17, -1
	s_and_b32 s16, s16, s17
	s_lshr_b32 s8, s16, 5
	s_mov_b32 s15, 0
	s_mov_b32 s1, 1
	s_mov_b32 s14, 9
	s_lshl_b32 s13, s22, 7
	s_add_i32 s12, s13, 0x1100
	s_add_i32 s13, s13, 0xf00
	s_lshl_b32 s16, s24, 5
	s_add_i32 s16, s16, s29
	s_lshl_b32 s16, s16, 7
	s_lshr_b32 s17, 0x80, s9
	s_mul_i32 s17, s17, s10
	s_add_i32 s16, s16, s17
	s_lshl_b32 s16, s16, 12
	s_add_u32 s4, s18, s16
	s_addc_u32 s5, s19, 0
	s_add_u32 s4, s4, 0x10600000
	s_addc_u32 s5, s5, 0
	s_lshl_b32 s16, s24, 15
	s_lshl_b32 s17, s23, 12
	s_add_i32 s16, s16, s17
	s_lshl_b32 s17, s16, 9
	s_lshl_b32 s28, s22, 7
	s_add_i32 s17, s17, s28
	s_add_u32 s6, s18, s17
	s_addc_u32 s7, s19, 0
	s_add_u32 s6, s6, 0x18600000
	s_addc_u32 s7, s7, 0
	s_lshl_b32 s17, s16, 4
	s_lshl_b32 s28, s22, 2
	s_add_i32 s17, s17, s28
	s_add_u32 s26, s18, s17
	s_addc_u32 s27, s19, 0
	s_add_u32 s26, s26, 0x1de00000
	s_addc_u32 s27, s27, 0
	s_add_i32 s24, s22, 9
.Lband_dec_done:
	s_mul_i32 s17, s23, 0x1600000
	s_add_u32 s2, s18, s17
	s_addc_u32 s3, s19, 0
	s_add_u32 s2, s2, 0x5600000
	s_addc_u32 s3, s3, 0
	s_lshl_b32 s11, 0x2c000, s9
	v_lshl_add_u32 v183, s8, 5, v163
	v_lshlrev_b32_e32 v183, s9, v183
	v_add_u32_e32 v176, s10, v183
	v_mul_u32_u24_e32 v177, 0x1600, v176
	v_add_u32_e32 v177, s13, v177
	v_lshl_add_u32 v177, v164, 4, v177
	global_load_dwordx4 v[130:133], v177, s[2:3]
	global_load_dwordx4 v[134:137], v177, s[2:3] offset:32
	global_load_dwordx4 v[138:141], v177, s[2:3] offset:64
	global_load_dwordx4 v[142:145], v177, s[2:3] offset:96
	v_lshlrev_b32_e32 v183, s9, v163
	v_add_u32_e32 v183, s10, v183
	v_mul_u32_u24_e32 v175, 0x1600, v183
	v_add_u32_e32 v175, s12, v175
	v_lshl_add_u32 v175, v164, 4, v175
	s_add_i32 s16, s8, -4
	s_max_i32 s16, s16, 0
	s_mul_i32 s17, s16, s11
	v_add_u32_e32 v177, s17, v175
	global_load_dwordx4 v[2:5], v177, s[2:3]
	global_load_dwordx4 v[6:9], v177, s[2:3] offset:32
	global_load_dwordx4 v[10:13], v177, s[2:3] offset:64
	global_load_dwordx4 v[14:17], v177, s[2:3] offset:96
	s_add_i32 s16, s8, -4
	s_max_i32 s16, s16, 0
	s_lshl_b32 s17, s16, 12
	v_add_u32_e32 v177, s17, v162
	global_load_dwordx4 v[82:85], v177, s[4:5]
	global_load_dwordx4 v[86:89], v177, s[4:5] offset:1024
	global_load_dwordx4 v[90:93], v177, s[4:5] offset:2048
	global_load_dwordx4 v[94:97], v177, s[4:5] offset:3072
	s_add_i32 s16, s8, -3
	s_max_i32 s16, s16, 0
	s_mul_i32 s17, s16, s11
	v_add_u32_e32 v177, s17, v175
	global_load_dwordx4 v[18:21], v177, s[2:3]
	global_load_dwordx4 v[22:25], v177, s[2:3] offset:32
	global_load_dwordx4 v[26:29], v177, s[2:3] offset:64
	global_load_dwordx4 v[30:33], v177, s[2:3] offset:96
	s_add_i32 s16, s8, -3
	s_max_i32 s16, s16, 0
	s_lshl_b32 s17, s16, 12
	v_add_u32_e32 v177, s17, v162
	global_load_dwordx4 v[98:101], v177, s[4:5]
	global_load_dwordx4 v[102:105], v177, s[4:5] offset:1024
	global_load_dwordx4 v[106:109], v177, s[4:5] offset:2048
	global_load_dwordx4 v[110:113], v177, s[4:5] offset:3072
	s_add_i32 s16, s8, -2
	s_max_i32 s16, s16, 0
	s_mul_i32 s17, s16, s11
	v_add_u32_e32 v177, s17, v175
	global_load_dwordx4 v[34:37], v177, s[2:3]
	global_load_dwordx4 v[38:41], v177, s[2:3] offset:32
	global_load_dwordx4 v[42:45], v177, s[2:3] offset:64
	global_load_dwordx4 v[46:49], v177, s[2:3] offset:96
	s_add_i32 s16, s8, -2
	s_max_i32 s16, s16, 0
	s_lshl_b32 s17, s16, 12
	v_add_u32_e32 v177, s17, v162
	global_load_dwordx4 v[114:117], v177, s[4:5]
	global_load_dwordx4 v[118:121], v177, s[4:5] offset:1024
	global_load_dwordx4 v[122:125], v177, s[4:5] offset:2048
	global_load_dwordx4 v[126:129], v177, s[4:5] offset:3072
	s_add_i32 s16, s8, -1
	s_max_i32 s16, s16, 0
	s_mul_i32 s17, s16, s11
	v_add_u32_e32 v177, s17, v175
	global_load_dwordx4 v[50:53], v177, s[2:3]
	global_load_dwordx4 v[54:57], v177, s[2:3] offset:32
	global_load_dwordx4 v[58:61], v177, s[2:3] offset:64
	global_load_dwordx4 v[62:65], v177, s[2:3] offset:96
	s_add_i32 s16, s8, 0
	s_max_i32 s16, s16, 0
	s_mul_i32 s17, s16, s11
	v_add_u32_e32 v177, s17, v175
	global_load_dwordx4 v[66:69], v177, s[2:3]
	global_load_dwordx4 v[70:73], v177, s[2:3] offset:32
	global_load_dwordx4 v[74:77], v177, s[2:3] offset:64
	global_load_dwordx4 v[78:81], v177, s[2:3] offset:96
	v_cvt_f32_i32_e32 v167, s24
	v_mul_f32_e32 v167, 0xbf2aaaab, v167
	v_exp_f32_e32 v167, v167
	v_cvt_f32_i32_e32 v168, v170
	v_mul_f32_e32 v167, 0x3fb8aa3b, v167
	v_ldexp_f32 v167, v167, s9
	v_mul_f32_e64 v168, -v167, v168
	v_add_u32_e32 v174, s15, v170
	v_lshlrev_b32_e32 v218, s14, v176
	v_lshl_add_u32 v218, v164, 3, v218
	v_lshlrev_b32_e32 v219, 4, v176
	v_mov_b32_e32 v165, 0xf149f2ca
	v_mov_b32_e32 v166, 0
	v_mov_b32_e32 v146, 0
	v_mov_b32_e32 v147, 0
	v_mov_b32_e32 v148, 0
	v_mov_b32_e32 v149, 0
	v_mov_b32_e32 v150, 0
	v_mov_b32_e32 v151, 0
	v_mov_b32_e32 v152, 0
	v_mov_b32_e32 v153, 0
	v_mov_b32_e32 v154, 0
	v_mov_b32_e32 v155, 0
	v_mov_b32_e32 v156, 0
	v_mov_b32_e32 v157, 0
	v_mov_b32_e32 v158, 0
	v_mov_b32_e32 v159, 0
	v_mov_b32_e32 v160, 0
	v_mov_b32_e32 v161, 0
	v_mov_b32_e32 v184, 0
	v_mov_b32_e32 v185, 0
	v_mov_b32_e32 v186, 0
	v_mov_b32_e32 v187, 0
	v_mov_b32_e32 v188, 0
	v_mov_b32_e32 v189, 0
	v_mov_b32_e32 v190, 0
	v_mov_b32_e32 v191, 0
	v_mov_b32_e32 v192, 0
	v_mov_b32_e32 v193, 0
	v_mov_b32_e32 v194, 0
	v_mov_b32_e32 v195, 0
	v_mov_b32_e32 v196, 0
	v_mov_b32_e32 v197, 0
	v_mov_b32_e32 v198, 0
	v_mov_b32_e32 v199, 0
	s_cmp_lt_i32 s8, 4
	s_cbranch_scc1 .Lband_s0a
	s_waitcnt vmcnt(28)
	v_mfma_f32_32x32x16_bf16 v[200:215], v[2:5], v[130:133], 0
	v_mfma_f32_32x32x16_bf16 v[200:215], v[6:9], v[134:137], v[200:215]
	v_mfma_f32_32x32x16_bf16 v[200:215], v[10:13], v[138:141], v[200:215]
	v_mfma_f32_32x32x16_bf16 v[200:215], v[14:17], v[142:145], v[200:215]
.Lband_s0a:
	s_add_i32 s16, s8, -1
	s_max_i32 s16, s16, 0
	s_lshl_b32 s17, s16, 12
	v_add_u32_e32 v177, s17, v162
	global_load_dwordx4 v[2:5], v177, s[4:5]
	global_load_dwordx4 v[6:9], v177, s[4:5] offset:1024
	global_load_dwordx4 v[10:13], v177, s[4:5] offset:2048
	global_load_dwordx4 v[14:17], v177, s[4:5] offset:3072
	s_cmp_lt_i32 s8, 4
	s_cbranch_scc1 .Lband_s0b
	v_fmamk_f32 v169, v167, 0xc3000000, v168
	s_nop 7
	s_nop 4
	v_fmamk_f32 v183, v167, 0x00000000, v169
	v_fmamk_f32 v200, v200, 0x3e38aa3b, v183
	v_fmamk_f32 v225, v167, 0x3f800000, v169
	v_fmamk_f32 v201, v201, 0x3e38aa3b, v225
	v_fmamk_f32 v183, v167, 0x40000000, v169
	v_fmamk_f32 v202, v202, 0x3e38aa3b, v183
	v_fmamk_f32 v225, v167, 0x40400000, v169
	v_fmamk_f32 v203, v203, 0x3e38aa3b, v225
	v_fmamk_f32 v183, v167, 0x41000000, v169
	v_fmamk_f32 v204, v204, 0x3e38aa3b, v183
	v_fmamk_f32 v225, v167, 0x41100000, v169
	v_fmamk_f32 v205, v205, 0x3e38aa3b, v225
	v_fmamk_f32 v183, v167, 0x41200000, v169
	v_fmamk_f32 v206, v206, 0x3e38aa3b, v183
	v_fmamk_f32 v225, v167, 0x41300000, v169
	v_fmamk_f32 v207, v207, 0x3e38aa3b, v225
	v_fmamk_f32 v183, v167, 0x41800000, v169
	v_fmamk_f32 v208, v208, 0x3e38aa3b, v183
	v_fmamk_f32 v225, v167, 0x41880000, v169
	v_fmamk_f32 v209, v209, 0x3e38aa3b, v225
	v_fmamk_f32 v183, v167, 0x41900000, v169
	v_fmamk_f32 v210, v210, 0x3e38aa3b, v183
	v_fmamk_f32 v225, v167, 0x41980000, v169
	v_fmamk_f32 v211, v211, 0x3e38aa3b, v225
	v_fmamk_f32 v183, v167, 0x41c00000, v169
	v_fmamk_f32 v212, v212, 0x3e38aa3b, v183
	v_fmamk_f32 v225, v167, 0x41c80000, v169
	v_fmamk_f32 v213, v213, 0x3e38aa3b, v225
	v_fmamk_f32 v183, v167, 0x41d00000, v169
	v_fmamk_f32 v214, v214, 0x3e38aa3b, v183
	v_fmamk_f32 v225, v167, 0x41d80000, v169
	v_fmamk_f32 v215, v215, 0x3e38aa3b, v225
	v_cmp_ge_i32_e64 s[16:17], 0, v174
	v_cmp_ge_i32_e64 s[22:23], 1, v174
	v_cmp_ge_i32_e64 s[24:25], 2, v174
	v_cmp_ge_i32_e64 s[28:29], 3, v174
	v_cmp_ge_i32_e32 vcc, 8, v174
	v_cndmask_b32_e64 v200, v227, v200, s[16:17]
	v_cndmask_b32_e64 v201, v227, v201, s[22:23]
	v_cndmask_b32_e64 v202, v227, v202, s[24:25]
	v_cndmask_b32_e64 v203, v227, v203, s[28:29]
	v_cndmask_b32_e64 v204, v227, v204, vcc
	v_cmp_ge_i32_e64 s[16:17], 9, v174
	v_cmp_ge_i32_e64 s[22:23], 10, v174
	v_cmp_ge_i32_e64 s[24:25], 11, v174
	v_cmp_ge_i32_e64 s[28:29], 16, v174
	v_cmp_ge_i32_e32 vcc, 17, v174
	v_cndmask_b32_e64 v205, v227, v205, s[16:17]
	v_cndmask_b32_e64 v206, v227, v206, s[22:23]
	v_cndmask_b32_e64 v207, v227, v207, s[24:25]
	v_cndmask_b32_e64 v208, v227, v208, s[28:29]
	v_cndmask_b32_e64 v209, v227, v209, vcc
	v_cmp_ge_i32_e64 s[16:17], 18, v174
	v_cmp_ge_i32_e64 s[22:23], 19, v174
	v_cmp_ge_i32_e64 s[24:25], 24, v174
	v_cmp_ge_i32_e64 s[28:29], 25, v174
	v_cmp_ge_i32_e32 vcc, 26, v174
	v_cndmask_b32_e64 v210, v227, v210, s[16:17]
	v_cndmask_b32_e64 v211, v227, v211, s[22:23]
	v_cndmask_b32_e64 v212, v227, v212, s[24:25]
	v_cndmask_b32_e64 v213, v227, v213, s[28:29]
	v_cndmask_b32_e64 v214, v227, v214, vcc
	v_cmp_ge_i32_e64 s[16:17], 27, v174
	s_nop 1
	v_cndmask_b32_e64 v215, v227, v215, s[16:17]
	v_max3_f32 v183, v200, v201, v202
	v_max3_f32 v225, v203, v204, v205
	v_max3_f32 v216, v206, v207, v208
	v_max3_f32 v217, v209, v210, v211
	v_max3_f32 v236, v212, v213, v214
	v_max3_f32 v183, v183, v225, v216
	v_max3_f32 v217, v217, v236, v215
	v_max_f32_e32 v183, v183, v217
	ds_bpermute_b32 v225, v249, v183
	s_waitcnt lgkmcnt(0)
	v_max3_f32 v225, v225, v183, v165
	v_sub_f32_e32 v216, v165, v225
	v_exp_f32_e32 v216, v216
	v_mov_b32_e32 v165, v225
	v_sub_f32_e32 v200, v200, v225
	v_exp_f32_e32 v200, v200
	v_sub_f32_e32 v201, v201, v225
	v_exp_f32_e32 v201, v201
	v_sub_f32_e32 v202, v202, v225
	v_exp_f32_e32 v202, v202
	v_sub_f32_e32 v203, v203, v225
	v_exp_f32_e32 v203, v203
	v_sub_f32_e32 v204, v204, v225
	v_exp_f32_e32 v204, v204
	v_sub_f32_e32 v205, v205, v225
	v_exp_f32_e32 v205, v205
	v_sub_f32_e32 v206, v206, v225
	v_exp_f32_e32 v206, v206
	v_sub_f32_e32 v207, v207, v225
	v_exp_f32_e32 v207, v207
	v_sub_f32_e32 v208, v208, v225
	v_exp_f32_e32 v208, v208
	v_sub_f32_e32 v209, v209, v225
	v_exp_f32_e32 v209, v209
	v_sub_f32_e32 v210, v210, v225
	v_exp_f32_e32 v210, v210
	v_sub_f32_e32 v211, v211, v225
	v_exp_f32_e32 v211, v211
	v_sub_f32_e32 v212, v212, v225
	v_exp_f32_e32 v212, v212
	v_sub_f32_e32 v213, v213, v225
	v_exp_f32_e32 v213, v213
	v_sub_f32_e32 v214, v214, v225
	v_exp_f32_e32 v214, v214
	v_sub_f32_e32 v215, v215, v225
	v_exp_f32_e32 v215, v215
	v_mul_f32_e32 v166, v166, v216
	v_pk_mul_f32 v[146:147], v[146:147], v[216:217] op_sel_hi:[1,0]
	v_pk_mul_f32 v[148:149], v[148:149], v[216:217] op_sel_hi:[1,0]
	v_pk_mul_f32 v[150:151], v[150:151], v[216:217] op_sel_hi:[1,0]
	v_pk_mul_f32 v[152:153], v[152:153], v[216:217] op_sel_hi:[1,0]
	v_pk_mul_f32 v[154:155], v[154:155], v[216:217] op_sel_hi:[1,0]
	v_pk_mul_f32 v[156:157], v[156:157], v[216:217] op_sel_hi:[1,0]
	v_pk_mul_f32 v[158:159], v[158:159], v[216:217] op_sel_hi:[1,0]
	v_pk_mul_f32 v[160:161], v[160:161], v[216:217] op_sel_hi:[1,0]
	v_pk_mul_f32 v[184:185], v[184:185], v[216:217] op_sel_hi:[1,0]
	v_pk_mul_f32 v[186:187], v[186:187], v[216:217] op_sel_hi:[1,0]
	v_pk_mul_f32 v[188:189], v[188:189], v[216:217] op_sel_hi:[1,0]
	v_pk_mul_f32 v[190:191], v[190:191], v[216:217] op_sel_hi:[1,0]
	v_pk_mul_f32 v[192:193], v[192:193], v[216:217] op_sel_hi:[1,0]
	v_pk_mul_f32 v[194:195], v[194:195], v[216:217] op_sel_hi:[1,0]
	v_pk_mul_f32 v[196:197], v[196:197], v[216:217] op_sel_hi:[1,0]
	v_pk_mul_f32 v[198:199], v[198:199], v[216:217] op_sel_hi:[1,0]
	v_add_f32_e32 v183, v200, v201
	v_add_f32_e32 v225, v202, v203
	v_add_f32_e32 v236, v204, v205
	v_add_f32_e32 v237, v206, v207
	v_add_f32_e32 v183, v183, v208
	v_add_f32_e32 v225, v225, v209
	v_add_f32_e32 v236, v236, v210
	v_add_f32_e32 v237, v237, v211
	v_add_f32_e32 v183, v183, v212
	v_add_f32_e32 v225, v225, v213
	v_add_f32_e32 v236, v236, v214
	v_add_f32_e32 v237, v237, v215
	v_add_f32_e32 v183, v183, v225
	v_add_f32_e32 v236, v236, v237
	v_add_f32_e32 v183, v183, v236
	v_add_f32_e32 v166, v166, v183
	v_cvt_pk_bf16_f32 v200, v200, v201
	v_cvt_pk_bf16_f32 v201, v202, v203
	v_cvt_pk_bf16_f32 v202, v204, v205
	v_cvt_pk_bf16_f32 v203, v206, v207
	v_cvt_pk_bf16_f32 v204, v208, v209
	v_cvt_pk_bf16_f32 v205, v210, v211
	v_cvt_pk_bf16_f32 v206, v212, v213
	v_cvt_pk_bf16_f32 v207, v214, v215
	s_waitcnt vmcnt(28)
	s_nop 1
	v_mfma_f32_32x32x16_bf16 v[146:161], v[82:85], v[200:203], v[146:161]
	v_mfma_f32_32x32x16_bf16 v[184:199], v[90:93], v[200:203], v[184:199]
	v_mfma_f32_32x32x16_bf16 v[146:161], v[86:89], v[204:207], v[146:161]
	v_mfma_f32_32x32x16_bf16 v[184:199], v[94:97], v[204:207], v[184:199]
.Lband_s0b:
	s_cmp_lt_i32 s8, 3
	s_cbranch_scc1 .Lband_s1a
	s_waitcnt vmcnt(24)
	v_mfma_f32_32x32x16_bf16 v[200:215], v[18:21], v[130:133], 0
	v_mfma_f32_32x32x16_bf16 v[200:215], v[22:25], v[134:137], v[200:215]
	v_mfma_f32_32x32x16_bf16 v[200:215], v[26:29], v[138:141], v[200:215]
	v_mfma_f32_32x32x16_bf16 v[200:215], v[30:33], v[142:145], v[200:215]
.Lband_s1a:
	s_add_i32 s16, s8, 0
	s_max_i32 s16, s16, 0
	s_lshl_b32 s17, s16, 12
	v_add_u32_e32 v177, s17, v162
	global_load_dwordx4 v[18:21], v177, s[4:5]
	global_load_dwordx4 v[22:25], v177, s[4:5] offset:1024
	global_load_dwordx4 v[26:29], v177, s[4:5] offset:2048
	global_load_dwordx4 v[30:33], v177, s[4:5] offset:3072
	s_cmp_lt_i32 s8, 3
	s_cbranch_scc1 .Lband_s1b
	v_fmamk_f32 v169, v167, 0xc2c00000, v168
	s_nop 7
	s_nop 4
	v_fmamk_f32 v183, v167, 0x00000000, v169
	v_fmamk_f32 v200, v200, 0x3e38aa3b, v183
	v_fmamk_f32 v225, v167, 0x3f800000, v169
	v_fmamk_f32 v201, v201, 0x3e38aa3b, v225
	v_fmamk_f32 v183, v167, 0x40000000, v169
	v_fmamk_f32 v202, v202, 0x3e38aa3b, v183
	v_fmamk_f32 v225, v167, 0x40400000, v169
	v_fmamk_f32 v203, v203, 0x3e38aa3b, v225
	v_fmamk_f32 v183, v167, 0x41000000, v169
	v_fmamk_f32 v204, v204, 0x3e38aa3b, v183
	v_fmamk_f32 v225, v167, 0x41100000, v169
	v_fmamk_f32 v205, v205, 0x3e38aa3b, v225
	v_fmamk_f32 v183, v167, 0x41200000, v169
	v_fmamk_f32 v206, v206, 0x3e38aa3b, v183
	v_fmamk_f32 v225, v167, 0x41300000, v169
	v_fmamk_f32 v207, v207, 0x3e38aa3b, v225
	v_fmamk_f32 v183, v167, 0x41800000, v169
	v_fmamk_f32 v208, v208, 0x3e38aa3b, v183
	v_fmamk_f32 v225, v167, 0x41880000, v169
	v_fmamk_f32 v209, v209, 0x3e38aa3b, v225
	v_fmamk_f32 v183, v167, 0x41900000, v169
	v_fmamk_f32 v210, v210, 0x3e38aa3b, v183
	v_fmamk_f32 v225, v167, 0x41980000, v169
	v_fmamk_f32 v211, v211, 0x3e38aa3b, v225
	v_fmamk_f32 v183, v167, 0x41c00000, v169
	v_fmamk_f32 v212, v212, 0x3e38aa3b, v183
	v_fmamk_f32 v225, v167, 0x41c80000, v169
	v_fmamk_f32 v213, v213, 0x3e38aa3b, v225
	v_fmamk_f32 v183, v167, 0x41d00000, v169
	v_fmamk_f32 v214, v214, 0x3e38aa3b, v183
	v_fmamk_f32 v225, v167, 0x41d80000, v169
	v_fmamk_f32 v215, v215, 0x3e38aa3b, v225
	v_max3_f32 v183, v200, v201, v202
	v_max3_f32 v225, v203, v204, v205
	v_max3_f32 v216, v206, v207, v208
	v_max3_f32 v217, v209, v210, v211
	v_max3_f32 v236, v212, v213, v214
	v_max3_f32 v183, v183, v225, v216
	v_max3_f32 v217, v217, v236, v215
	v_max_f32_e32 v183, v183, v217
	ds_bpermute_b32 v225, v249, v183
	s_waitcnt lgkmcnt(0)
	v_max3_f32 v225, v225, v183, v165
	v_sub_f32_e32 v216, v165, v225
	v_exp_f32_e32 v216, v216
	v_mov_b32_e32 v165, v225
	v_sub_f32_e32 v200, v200, v225
	v_exp_f32_e32 v200, v200
	v_sub_f32_e32 v201, v201, v225
	v_exp_f32_e32 v201, v201
	v_sub_f32_e32 v202, v202, v225
	v_exp_f32_e32 v202, v202
	v_sub_f32_e32 v203, v203, v225
	v_exp_f32_e32 v203, v203
	v_sub_f32_e32 v204, v204, v225
	v_exp_f32_e32 v204, v204
	v_sub_f32_e32 v205, v205, v225
	v_exp_f32_e32 v205, v205
	v_sub_f32_e32 v206, v206, v225
	v_exp_f32_e32 v206, v206
	v_sub_f32_e32 v207, v207, v225
	v_exp_f32_e32 v207, v207
	v_sub_f32_e32 v208, v208, v225
	v_exp_f32_e32 v208, v208
	v_sub_f32_e32 v209, v209, v225
	v_exp_f32_e32 v209, v209
	v_sub_f32_e32 v210, v210, v225
	v_exp_f32_e32 v210, v210
	v_sub_f32_e32 v211, v211, v225
	v_exp_f32_e32 v211, v211
	v_sub_f32_e32 v212, v212, v225
	v_exp_f32_e32 v212, v212
	v_sub_f32_e32 v213, v213, v225
	v_exp_f32_e32 v213, v213
	v_sub_f32_e32 v214, v214, v225
	v_exp_f32_e32 v214, v214
	v_sub_f32_e32 v215, v215, v225
	v_exp_f32_e32 v215, v215
	v_mul_f32_e32 v166, v166, v216
	v_pk_mul_f32 v[146:147], v[146:147], v[216:217] op_sel_hi:[1,0]
	v_pk_mul_f32 v[148:149], v[148:149], v[216:217] op_sel_hi:[1,0]
	v_pk_mul_f32 v[150:151], v[150:151], v[216:217] op_sel_hi:[1,0]
	v_pk_mul_f32 v[152:153], v[152:153], v[216:217] op_sel_hi:[1,0]
	v_pk_mul_f32 v[154:155], v[154:155], v[216:217] op_sel_hi:[1,0]
	v_pk_mul_f32 v[156:157], v[156:157], v[216:217] op_sel_hi:[1,0]
	v_pk_mul_f32 v[158:159], v[158:159], v[216:217] op_sel_hi:[1,0]
	v_pk_mul_f32 v[160:161], v[160:161], v[216:217] op_sel_hi:[1,0]
	v_pk_mul_f32 v[184:185], v[184:185], v[216:217] op_sel_hi:[1,0]
	v_pk_mul_f32 v[186:187], v[186:187], v[216:217] op_sel_hi:[1,0]
	v_pk_mul_f32 v[188:189], v[188:189], v[216:217] op_sel_hi:[1,0]
	v_pk_mul_f32 v[190:191], v[190:191], v[216:217] op_sel_hi:[1,0]
	v_pk_mul_f32 v[192:193], v[192:193], v[216:217] op_sel_hi:[1,0]
	v_pk_mul_f32 v[194:195], v[194:195], v[216:217] op_sel_hi:[1,0]
	v_pk_mul_f32 v[196:197], v[196:197], v[216:217] op_sel_hi:[1,0]
	v_pk_mul_f32 v[198:199], v[198:199], v[216:217] op_sel_hi:[1,0]
	v_add_f32_e32 v183, v200, v201
	v_add_f32_e32 v225, v202, v203
	v_add_f32_e32 v236, v204, v205
	v_add_f32_e32 v237, v206, v207
	v_add_f32_e32 v183, v183, v208
	v_add_f32_e32 v225, v225, v209
	v_add_f32_e32 v236, v236, v210
	v_add_f32_e32 v237, v237, v211
	v_add_f32_e32 v183, v183, v212
	v_add_f32_e32 v225, v225, v213
	v_add_f32_e32 v236, v236, v214
	v_add_f32_e32 v237, v237, v215
	v_add_f32_e32 v183, v183, v225
	v_add_f32_e32 v236, v236, v237
	v_add_f32_e32 v183, v183, v236
	v_add_f32_e32 v166, v166, v183
	v_cvt_pk_bf16_f32 v200, v200, v201
	v_cvt_pk_bf16_f32 v201, v202, v203
	v_cvt_pk_bf16_f32 v202, v204, v205
	v_cvt_pk_bf16_f32 v203, v206, v207
	v_cvt_pk_bf16_f32 v204, v208, v209
	v_cvt_pk_bf16_f32 v205, v210, v211
	v_cvt_pk_bf16_f32 v206, v212, v213
	v_cvt_pk_bf16_f32 v207, v214, v215
	s_waitcnt vmcnt(24)
	s_nop 1
	v_mfma_f32_32x32x16_bf16 v[146:161], v[98:101], v[200:203], v[146:161]
	v_mfma_f32_32x32x16_bf16 v[184:199], v[106:109], v[200:203], v[184:199]
	v_mfma_f32_32x32x16_bf16 v[146:161], v[102:105], v[204:207], v[146:161]
	v_mfma_f32_32x32x16_bf16 v[184:199], v[110:113], v[204:207], v[184:199]
.Lband_s1b:
	s_cmp_lt_i32 s8, 2
	s_cbranch_scc1 .Lband_s2a
	s_waitcnt vmcnt(20)
	v_mfma_f32_32x32x16_bf16 v[200:215], v[34:37], v[130:133], 0
	v_mfma_f32_32x32x16_bf16 v[200:215], v[38:41], v[134:137], v[200:215]
	v_mfma_f32_32x32x16_bf16 v[200:215], v[42:45], v[138:141], v[200:215]
	v_mfma_f32_32x32x16_bf16 v[200:215], v[46:49], v[142:145], v[200:215]
.Lband_s2a:
	s_cmp_lt_i32 s8, 2
	s_cbranch_scc1 .Lband_s2b
	v_fmamk_f32 v169, v167, 0xc2800000, v168
	s_nop 7
	s_nop 4
	v_fmamk_f32 v183, v167, 0x00000000, v169
	v_fmamk_f32 v200, v200, 0x3e38aa3b, v183
	v_fmamk_f32 v225, v167, 0x3f800000, v169
	v_fmamk_f32 v201, v201, 0x3e38aa3b, v225
	v_fmamk_f32 v183, v167, 0x40000000, v169
	v_fmamk_f32 v202, v202, 0x3e38aa3b, v183
	v_fmamk_f32 v225, v167, 0x40400000, v169
	v_fmamk_f32 v203, v203, 0x3e38aa3b, v225
	v_fmamk_f32 v183, v167, 0x41000000, v169
	v_fmamk_f32 v204, v204, 0x3e38aa3b, v183
	v_fmamk_f32 v225, v167, 0x41100000, v169
	v_fmamk_f32 v205, v205, 0x3e38aa3b, v225
	v_fmamk_f32 v183, v167, 0x41200000, v169
	v_fmamk_f32 v206, v206, 0x3e38aa3b, v183
	v_fmamk_f32 v225, v167, 0x41300000, v169
	v_fmamk_f32 v207, v207, 0x3e38aa3b, v225
	v_fmamk_f32 v183, v167, 0x41800000, v169
	v_fmamk_f32 v208, v208, 0x3e38aa3b, v183
	v_fmamk_f32 v225, v167, 0x41880000, v169
	v_fmamk_f32 v209, v209, 0x3e38aa3b, v225
	v_fmamk_f32 v183, v167, 0x41900000, v169
	v_fmamk_f32 v210, v210, 0x3e38aa3b, v183
	v_fmamk_f32 v225, v167, 0x41980000, v169
	v_fmamk_f32 v211, v211, 0x3e38aa3b, v225
	v_fmamk_f32 v183, v167, 0x41c00000, v169
	v_fmamk_f32 v212, v212, 0x3e38aa3b, v183
	v_fmamk_f32 v225, v167, 0x41c80000, v169
	v_fmamk_f32 v213, v213, 0x3e38aa3b, v225
	v_fmamk_f32 v183, v167, 0x41d00000, v169
	v_fmamk_f32 v214, v214, 0x3e38aa3b, v183
	v_fmamk_f32 v225, v167, 0x41d80000, v169
	v_fmamk_f32 v215, v215, 0x3e38aa3b, v225
	v_max3_f32 v183, v200, v201, v202
	v_max3_f32 v225, v203, v204, v205
	v_max3_f32 v216, v206, v207, v208
	v_max3_f32 v217, v209, v210, v211
	v_max3_f32 v236, v212, v213, v214
	v_max3_f32 v183, v183, v225, v216
	v_max3_f32 v217, v217, v236, v215
	v_max_f32_e32 v183, v183, v217
	ds_bpermute_b32 v225, v249, v183
	s_waitcnt lgkmcnt(0)
	v_max3_f32 v225, v225, v183, v165
	v_sub_f32_e32 v216, v165, v225
	v_exp_f32_e32 v216, v216
	v_mov_b32_e32 v165, v225
	v_sub_f32_e32 v200, v200, v225
	v_exp_f32_e32 v200, v200
	v_sub_f32_e32 v201, v201, v225
	v_exp_f32_e32 v201, v201
	v_sub_f32_e32 v202, v202, v225
	v_exp_f32_e32 v202, v202
	v_sub_f32_e32 v203, v203, v225
	v_exp_f32_e32 v203, v203
	v_sub_f32_e32 v204, v204, v225
	v_exp_f32_e32 v204, v204
	v_sub_f32_e32 v205, v205, v225
	v_exp_f32_e32 v205, v205
	v_sub_f32_e32 v206, v206, v225
	v_exp_f32_e32 v206, v206
	v_sub_f32_e32 v207, v207, v225
	v_exp_f32_e32 v207, v207
	v_sub_f32_e32 v208, v208, v225
	v_exp_f32_e32 v208, v208
	v_sub_f32_e32 v209, v209, v225
	v_exp_f32_e32 v209, v209
	v_sub_f32_e32 v210, v210, v225
	v_exp_f32_e32 v210, v210
	v_sub_f32_e32 v211, v211, v225
	v_exp_f32_e32 v211, v211
	v_sub_f32_e32 v212, v212, v225
	v_exp_f32_e32 v212, v212
	v_sub_f32_e32 v213, v213, v225
	v_exp_f32_e32 v213, v213
	v_sub_f32_e32 v214, v214, v225
	v_exp_f32_e32 v214, v214
	v_sub_f32_e32 v215, v215, v225
	v_exp_f32_e32 v215, v215
	v_mul_f32_e32 v166, v166, v216
	v_pk_mul_f32 v[146:147], v[146:147], v[216:217] op_sel_hi:[1,0]
	v_pk_mul_f32 v[148:149], v[148:149], v[216:217] op_sel_hi:[1,0]
	v_pk_mul_f32 v[150:151], v[150:151], v[216:217] op_sel_hi:[1,0]
	v_pk_mul_f32 v[152:153], v[152:153], v[216:217] op_sel_hi:[1,0]
	v_pk_mul_f32 v[154:155], v[154:155], v[216:217] op_sel_hi:[1,0]
	v_pk_mul_f32 v[156:157], v[156:157], v[216:217] op_sel_hi:[1,0]
	v_pk_mul_f32 v[158:159], v[158:159], v[216:217] op_sel_hi:[1,0]
	v_pk_mul_f32 v[160:161], v[160:161], v[216:217] op_sel_hi:[1,0]
	v_pk_mul_f32 v[184:185], v[184:185], v[216:217] op_sel_hi:[1,0]
	v_pk_mul_f32 v[186:187], v[186:187], v[216:217] op_sel_hi:[1,0]
	v_pk_mul_f32 v[188:189], v[188:189], v[216:217] op_sel_hi:[1,0]
	v_pk_mul_f32 v[190:191], v[190:191], v[216:217] op_sel_hi:[1,0]
	v_pk_mul_f32 v[192:193], v[192:193], v[216:217] op_sel_hi:[1,0]
	v_pk_mul_f32 v[194:195], v[194:195], v[216:217] op_sel_hi:[1,0]
	v_pk_mul_f32 v[196:197], v[196:197], v[216:217] op_sel_hi:[1,0]
	v_pk_mul_f32 v[198:199], v[198:199], v[216:217] op_sel_hi:[1,0]
	v_add_f32_e32 v183, v200, v201
	v_add_f32_e32 v225, v202, v203
	v_add_f32_e32 v236, v204, v205
	v_add_f32_e32 v237, v206, v207
	v_add_f32_e32 v183, v183, v208
	v_add_f32_e32 v225, v225, v209
	v_add_f32_e32 v236, v236, v210
	v_add_f32_e32 v237, v237, v211
	v_add_f32_e32 v183, v183, v212
	v_add_f32_e32 v225, v225, v213
	v_add_f32_e32 v236, v236, v214
	v_add_f32_e32 v237, v237, v215
	v_add_f32_e32 v183, v183, v225
	v_add_f32_e32 v236, v236, v237
	v_add_f32_e32 v183, v183, v236
	v_add_f32_e32 v166, v166, v183
	v_cvt_pk_bf16_f32 v200, v200, v201
	v_cvt_pk_bf16_f32 v201, v202, v203
	v_cvt_pk_bf16_f32 v202, v204, v205
	v_cvt_pk_bf16_f32 v203, v206, v207
	v_cvt_pk_bf16_f32 v204, v208, v209
	v_cvt_pk_bf16_f32 v205, v210, v211
	v_cvt_pk_bf16_f32 v206, v212, v213
	v_cvt_pk_bf16_f32 v207, v214, v215
	s_waitcnt vmcnt(16)
	s_nop 1
	v_mfma_f32_32x32x16_bf16 v[146:161], v[114:117], v[200:203], v[146:161]
	v_mfma_f32_32x32x16_bf16 v[184:199], v[122:125], v[200:203], v[184:199]
	v_mfma_f32_32x32x16_bf16 v[146:161], v[118:121], v[204:207], v[146:161]
	v_mfma_f32_32x32x16_bf16 v[184:199], v[126:129], v[204:207], v[184:199]
.Lband_s2b:
	s_cmp_lt_i32 s8, 1
	s_cbranch_scc1 .Lband_s3a
	s_waitcnt vmcnt(12)
	v_mfma_f32_32x32x16_bf16 v[200:215], v[50:53], v[130:133], 0
	v_mfma_f32_32x32x16_bf16 v[200:215], v[54:57], v[134:137], v[200:215]
	v_mfma_f32_32x32x16_bf16 v[200:215], v[58:61], v[138:141], v[200:215]
	v_mfma_f32_32x32x16_bf16 v[200:215], v[62:65], v[142:145], v[200:215]
.Lband_s3a:
	s_cmp_lt_i32 s8, 1
	s_cbranch_scc1 .Lband_s3b
	v_fmamk_f32 v169, v167, 0xc2000000, v168
	s_nop 7
	s_nop 4
	v_fmamk_f32 v183, v167, 0x00000000, v169
	v_fmamk_f32 v200, v200, 0x3e38aa3b, v183
	v_fmamk_f32 v225, v167, 0x3f800000, v169
	v_fmamk_f32 v201, v201, 0x3e38aa3b, v225
	v_fmamk_f32 v183, v167, 0x40000000, v169
	v_fmamk_f32 v202, v202, 0x3e38aa3b, v183
	v_fmamk_f32 v225, v167, 0x40400000, v169
	v_fmamk_f32 v203, v203, 0x3e38aa3b, v225
	v_fmamk_f32 v183, v167, 0x41000000, v169
	v_fmamk_f32 v204, v204, 0x3e38aa3b, v183
	v_fmamk_f32 v225, v167, 0x41100000, v169
	v_fmamk_f32 v205, v205, 0x3e38aa3b, v225
	v_fmamk_f32 v183, v167, 0x41200000, v169
	v_fmamk_f32 v206, v206, 0x3e38aa3b, v183
	v_fmamk_f32 v225, v167, 0x41300000, v169
	v_fmamk_f32 v207, v207, 0x3e38aa3b, v225
	v_fmamk_f32 v183, v167, 0x41800000, v169
	v_fmamk_f32 v208, v208, 0x3e38aa3b, v183
	v_fmamk_f32 v225, v167, 0x41880000, v169
	v_fmamk_f32 v209, v209, 0x3e38aa3b, v225
	v_fmamk_f32 v183, v167, 0x41900000, v169
	v_fmamk_f32 v210, v210, 0x3e38aa3b, v183
	v_fmamk_f32 v225, v167, 0x41980000, v169
	v_fmamk_f32 v211, v211, 0x3e38aa3b, v225
	v_fmamk_f32 v183, v167, 0x41c00000, v169
	v_fmamk_f32 v212, v212, 0x3e38aa3b, v183
	v_fmamk_f32 v225, v167, 0x41c80000, v169
	v_fmamk_f32 v213, v213, 0x3e38aa3b, v225
	v_fmamk_f32 v183, v167, 0x41d00000, v169
	v_fmamk_f32 v214, v214, 0x3e38aa3b, v183
	v_fmamk_f32 v225, v167, 0x41d80000, v169
	v_fmamk_f32 v215, v215, 0x3e38aa3b, v225
	v_max3_f32 v183, v200, v201, v202
	v_max3_f32 v225, v203, v204, v205
	v_max3_f32 v216, v206, v207, v208
	v_max3_f32 v217, v209, v210, v211
	v_max3_f32 v236, v212, v213, v214
	v_max3_f32 v183, v183, v225, v216
	v_max3_f32 v217, v217, v236, v215
	v_max_f32_e32 v183, v183, v217
	ds_bpermute_b32 v225, v249, v183
	s_waitcnt lgkmcnt(0)
	v_max3_f32 v225, v225, v183, v165
	v_sub_f32_e32 v216, v165, v225
	v_exp_f32_e32 v216, v216
	v_mov_b32_e32 v165, v225
	v_sub_f32_e32 v200, v200, v225
	v_exp_f32_e32 v200, v200
	v_sub_f32_e32 v201, v201, v225
	v_exp_f32_e32 v201, v201
	v_sub_f32_e32 v202, v202, v225
	v_exp_f32_e32 v202, v202
	v_sub_f32_e32 v203, v203, v225
	v_exp_f32_e32 v203, v203
	v_sub_f32_e32 v204, v204, v225
	v_exp_f32_e32 v204, v204
	v_sub_f32_e32 v205, v205, v225
	v_exp_f32_e32 v205, v205
	v_sub_f32_e32 v206, v206, v225
	v_exp_f32_e32 v206, v206
	v_sub_f32_e32 v207, v207, v225
	v_exp_f32_e32 v207, v207
	v_sub_f32_e32 v208, v208, v225
	v_exp_f32_e32 v208, v208
	v_sub_f32_e32 v209, v209, v225
	v_exp_f32_e32 v209, v209
	v_sub_f32_e32 v210, v210, v225
	v_exp_f32_e32 v210, v210
	v_sub_f32_e32 v211, v211, v225
	v_exp_f32_e32 v211, v211
	v_sub_f32_e32 v212, v212, v225
	v_exp_f32_e32 v212, v212
	v_sub_f32_e32 v213, v213, v225
	v_exp_f32_e32 v213, v213
	v_sub_f32_e32 v214, v214, v225
	v_exp_f32_e32 v214, v214
	v_sub_f32_e32 v215, v215, v225
	v_exp_f32_e32 v215, v215
	v_mul_f32_e32 v166, v166, v216
	v_pk_mul_f32 v[146:147], v[146:147], v[216:217] op_sel_hi:[1,0]
	v_pk_mul_f32 v[148:149], v[148:149], v[216:217] op_sel_hi:[1,0]
	v_pk_mul_f32 v[150:151], v[150:151], v[216:217] op_sel_hi:[1,0]
	v_pk_mul_f32 v[152:153], v[152:153], v[216:217] op_sel_hi:[1,0]
	v_pk_mul_f32 v[154:155], v[154:155], v[216:217] op_sel_hi:[1,0]
	v_pk_mul_f32 v[156:157], v[156:157], v[216:217] op_sel_hi:[1,0]
	v_pk_mul_f32 v[158:159], v[158:159], v[216:217] op_sel_hi:[1,0]
	v_pk_mul_f32 v[160:161], v[160:161], v[216:217] op_sel_hi:[1,0]
	v_pk_mul_f32 v[184:185], v[184:185], v[216:217] op_sel_hi:[1,0]
	v_pk_mul_f32 v[186:187], v[186:187], v[216:217] op_sel_hi:[1,0]
	v_pk_mul_f32 v[188:189], v[188:189], v[216:217] op_sel_hi:[1,0]
	v_pk_mul_f32 v[190:191], v[190:191], v[216:217] op_sel_hi:[1,0]
	v_pk_mul_f32 v[192:193], v[192:193], v[216:217] op_sel_hi:[1,0]
	v_pk_mul_f32 v[194:195], v[194:195], v[216:217] op_sel_hi:[1,0]
	v_pk_mul_f32 v[196:197], v[196:197], v[216:217] op_sel_hi:[1,0]
	v_pk_mul_f32 v[198:199], v[198:199], v[216:217] op_sel_hi:[1,0]
	v_add_f32_e32 v183, v200, v201
	v_add_f32_e32 v225, v202, v203
	v_add_f32_e32 v236, v204, v205
	v_add_f32_e32 v237, v206, v207
	v_add_f32_e32 v183, v183, v208
	v_add_f32_e32 v225, v225, v209
	v_add_f32_e32 v236, v236, v210
	v_add_f32_e32 v237, v237, v211
	v_add_f32_e32 v183, v183, v212
	v_add_f32_e32 v225, v225, v213
	v_add_f32_e32 v236, v236, v214
	v_add_f32_e32 v237, v237, v215
	v_add_f32_e32 v183, v183, v225
	v_add_f32_e32 v236, v236, v237
	v_add_f32_e32 v183, v183, v236
	v_add_f32_e32 v166, v166, v183
	v_cvt_pk_bf16_f32 v200, v200, v201
	v_cvt_pk_bf16_f32 v201, v202, v203
	v_cvt_pk_bf16_f32 v202, v204, v205
	v_cvt_pk_bf16_f32 v203, v206, v207
	v_cvt_pk_bf16_f32 v204, v208, v209
	v_cvt_pk_bf16_f32 v205, v210, v211
	v_cvt_pk_bf16_f32 v206, v212, v213
	v_cvt_pk_bf16_f32 v207, v214, v215
	s_waitcnt vmcnt(4)
	s_nop 1
	v_mfma_f32_32x32x16_bf16 v[146:161], v[2:5], v[200:203], v[146:161]
	v_mfma_f32_32x32x16_bf16 v[184:199], v[10:13], v[200:203], v[184:199]
	v_mfma_f32_32x32x16_bf16 v[146:161], v[6:9], v[204:207], v[146:161]
	v_mfma_f32_32x32x16_bf16 v[184:199], v[14:17], v[204:207], v[184:199]
.Lband_s3b:
	s_waitcnt vmcnt(8)
	v_mfma_f32_32x32x16_bf16 v[200:215], v[66:69], v[130:133], 0
	v_mfma_f32_32x32x16_bf16 v[200:215], v[70:73], v[134:137], v[200:215]
	v_mfma_f32_32x32x16_bf16 v[200:215], v[74:77], v[138:141], v[200:215]
	v_mfma_f32_32x32x16_bf16 v[200:215], v[78:81], v[142:145], v[200:215]
	v_mov_b32_e32 v169, v168
	s_nop 7
	s_nop 4
	v_fmamk_f32 v183, v167, 0x00000000, v169
	v_fmamk_f32 v200, v200, 0x3e38aa3b, v183
	v_fmamk_f32 v225, v167, 0x3f800000, v169
	v_fmamk_f32 v201, v201, 0x3e38aa3b, v225
	v_fmamk_f32 v183, v167, 0x40000000, v169
	v_fmamk_f32 v202, v202, 0x3e38aa3b, v183
	v_fmamk_f32 v225, v167, 0x40400000, v169
	v_fmamk_f32 v203, v203, 0x3e38aa3b, v225
	v_fmamk_f32 v183, v167, 0x41000000, v169
	v_fmamk_f32 v204, v204, 0x3e38aa3b, v183
	v_fmamk_f32 v225, v167, 0x41100000, v169
	v_fmamk_f32 v205, v205, 0x3e38aa3b, v225
	v_fmamk_f32 v183, v167, 0x41200000, v169
	v_fmamk_f32 v206, v206, 0x3e38aa3b, v183
	v_fmamk_f32 v225, v167, 0x41300000, v169
	v_fmamk_f32 v207, v207, 0x3e38aa3b, v225
	v_fmamk_f32 v183, v167, 0x41800000, v169
	v_fmamk_f32 v208, v208, 0x3e38aa3b, v183
	v_fmamk_f32 v225, v167, 0x41880000, v169
	v_fmamk_f32 v209, v209, 0x3e38aa3b, v225
	v_fmamk_f32 v183, v167, 0x41900000, v169
	v_fmamk_f32 v210, v210, 0x3e38aa3b, v183
	v_fmamk_f32 v225, v167, 0x41980000, v169
	v_fmamk_f32 v211, v211, 0x3e38aa3b, v225
	v_fmamk_f32 v183, v167, 0x41c00000, v169
	v_fmamk_f32 v212, v212, 0x3e38aa3b, v183
	v_fmamk_f32 v225, v167, 0x41c80000, v169
	v_fmamk_f32 v213, v213, 0x3e38aa3b, v225
	v_fmamk_f32 v183, v167, 0x41d00000, v169
	v_fmamk_f32 v214, v214, 0x3e38aa3b, v183
	v_fmamk_f32 v225, v167, 0x41d80000, v169
	v_fmamk_f32 v215, v215, 0x3e38aa3b, v225
	v_cmp_le_i32_e64 s[16:17], 0, v170
	v_cmp_le_i32_e64 s[22:23], 1, v170
	v_cmp_le_i32_e64 s[24:25], 2, v170
	v_cmp_le_i32_e64 s[28:29], 3, v170
	v_cmp_le_i32_e32 vcc, 8, v170
	v_cndmask_b32_e64 v200, v227, v200, s[16:17]
	v_cndmask_b32_e64 v201, v227, v201, s[22:23]
	v_cndmask_b32_e64 v202, v227, v202, s[24:25]
	v_cndmask_b32_e64 v203, v227, v203, s[28:29]
	v_cndmask_b32_e64 v204, v227, v204, vcc
	v_cmp_le_i32_e64 s[16:17], 9, v170
	v_cmp_le_i32_e64 s[22:23], 10, v170
	v_cmp_le_i32_e64 s[24:25], 11, v170
	v_cmp_le_i32_e64 s[28:29], 16, v170
	v_cmp_le_i32_e32 vcc, 17, v170
	v_cndmask_b32_e64 v205, v227, v205, s[16:17]
	v_cndmask_b32_e64 v206, v227, v206, s[22:23]
	v_cndmask_b32_e64 v207, v227, v207, s[24:25]
	v_cndmask_b32_e64 v208, v227, v208, s[28:29]
	v_cndmask_b32_e64 v209, v227, v209, vcc
	v_cmp_le_i32_e64 s[16:17], 18, v170
	v_cmp_le_i32_e64 s[22:23], 19, v170
	v_cmp_le_i32_e64 s[24:25], 24, v170
	v_cmp_le_i32_e64 s[28:29], 25, v170
	v_cmp_le_i32_e32 vcc, 26, v170
	v_cndmask_b32_e64 v210, v227, v210, s[16:17]
	v_cndmask_b32_e64 v211, v227, v211, s[22:23]
	v_cndmask_b32_e64 v212, v227, v212, s[24:25]
	v_cndmask_b32_e64 v213, v227, v213, s[28:29]
	v_cndmask_b32_e64 v214, v227, v214, vcc
	v_cmp_le_i32_e64 s[16:17], 27, v170
	s_nop 1
	v_cndmask_b32_e64 v215, v227, v215, s[16:17]
	v_max3_f32 v183, v200, v201, v202
	v_max3_f32 v225, v203, v204, v205
	v_max3_f32 v216, v206, v207, v208
	v_max3_f32 v217, v209, v210, v211
	v_max3_f32 v236, v212, v213, v214
	v_max3_f32 v183, v183, v225, v216
	v_max3_f32 v217, v217, v236, v215
	v_max_f32_e32 v183, v183, v217
	ds_bpermute_b32 v225, v249, v183
	s_waitcnt lgkmcnt(0)
	v_max3_f32 v225, v225, v183, v165
	v_sub_f32_e32 v216, v165, v225
	v_exp_f32_e32 v216, v216
	v_mov_b32_e32 v165, v225
	v_sub_f32_e32 v200, v200, v225
	v_exp_f32_e32 v200, v200
	v_sub_f32_e32 v201, v201, v225
	v_exp_f32_e32 v201, v201
	v_sub_f32_e32 v202, v202, v225
	v_exp_f32_e32 v202, v202
	v_sub_f32_e32 v203, v203, v225
	v_exp_f32_e32 v203, v203
	v_sub_f32_e32 v204, v204, v225
	v_exp_f32_e32 v204, v204
	v_sub_f32_e32 v205, v205, v225
	v_exp_f32_e32 v205, v205
	v_sub_f32_e32 v206, v206, v225
	v_exp_f32_e32 v206, v206
	v_sub_f32_e32 v207, v207, v225
	v_exp_f32_e32 v207, v207
	v_sub_f32_e32 v208, v208, v225
	v_exp_f32_e32 v208, v208
	v_sub_f32_e32 v209, v209, v225
	v_exp_f32_e32 v209, v209
	v_sub_f32_e32 v210, v210, v225
	v_exp_f32_e32 v210, v210
	v_sub_f32_e32 v211, v211, v225
	v_exp_f32_e32 v211, v211
	v_sub_f32_e32 v212, v212, v225
	v_exp_f32_e32 v212, v212
	v_sub_f32_e32 v213, v213, v225
	v_exp_f32_e32 v213, v213
	v_sub_f32_e32 v214, v214, v225
	v_exp_f32_e32 v214, v214
	v_sub_f32_e32 v215, v215, v225
	v_exp_f32_e32 v215, v215
	v_mul_f32_e32 v166, v166, v216
	v_pk_mul_f32 v[146:147], v[146:147], v[216:217] op_sel_hi:[1,0]
	v_pk_mul_f32 v[148:149], v[148:149], v[216:217] op_sel_hi:[1,0]
	v_pk_mul_f32 v[150:151], v[150:151], v[216:217] op_sel_hi:[1,0]
	v_pk_mul_f32 v[152:153], v[152:153], v[216:217] op_sel_hi:[1,0]
	v_pk_mul_f32 v[154:155], v[154:155], v[216:217] op_sel_hi:[1,0]
	v_pk_mul_f32 v[156:157], v[156:157], v[216:217] op_sel_hi:[1,0]
	v_pk_mul_f32 v[158:159], v[158:159], v[216:217] op_sel_hi:[1,0]
	v_pk_mul_f32 v[160:161], v[160:161], v[216:217] op_sel_hi:[1,0]
	v_pk_mul_f32 v[184:185], v[184:185], v[216:217] op_sel_hi:[1,0]
	v_pk_mul_f32 v[186:187], v[186:187], v[216:217] op_sel_hi:[1,0]
	v_pk_mul_f32 v[188:189], v[188:189], v[216:217] op_sel_hi:[1,0]
	v_pk_mul_f32 v[190:191], v[190:191], v[216:217] op_sel_hi:[1,0]
	v_pk_mul_f32 v[192:193], v[192:193], v[216:217] op_sel_hi:[1,0]
	v_pk_mul_f32 v[194:195], v[194:195], v[216:217] op_sel_hi:[1,0]
	v_pk_mul_f32 v[196:197], v[196:197], v[216:217] op_sel_hi:[1,0]
	v_pk_mul_f32 v[198:199], v[198:199], v[216:217] op_sel_hi:[1,0]
	v_add_f32_e32 v183, v200, v201
	v_add_f32_e32 v225, v202, v203
	v_add_f32_e32 v236, v204, v205
	v_add_f32_e32 v237, v206, v207
	v_add_f32_e32 v183, v183, v208
	v_add_f32_e32 v225, v225, v209
	v_add_f32_e32 v236, v236, v210
	v_add_f32_e32 v237, v237, v211
	v_add_f32_e32 v183, v183, v212
	v_add_f32_e32 v225, v225, v213
	v_add_f32_e32 v236, v236, v214
	v_add_f32_e32 v237, v237, v215
	v_add_f32_e32 v183, v183, v225
	v_add_f32_e32 v236, v236, v237
	v_add_f32_e32 v183, v183, v236
	v_add_f32_e32 v166, v166, v183
	v_cvt_pk_bf16_f32 v200, v200, v201
	v_cvt_pk_bf16_f32 v201, v202, v203
	v_cvt_pk_bf16_f32 v202, v204, v205
	v_cvt_pk_bf16_f32 v203, v206, v207
	v_cvt_pk_bf16_f32 v204, v208, v209
	v_cvt_pk_bf16_f32 v205, v210, v211
	v_cvt_pk_bf16_f32 v206, v212, v213
	v_cvt_pk_bf16_f32 v207, v214, v215
	s_waitcnt vmcnt(0)
	s_nop 1
	v_mfma_f32_32x32x16_bf16 v[146:161], v[18:21], v[200:203], v[146:161]
	v_mfma_f32_32x32x16_bf16 v[184:199], v[26:29], v[200:203], v[184:199]
	v_mfma_f32_32x32x16_bf16 v[146:161], v[22:25], v[204:207], v[146:161]
	v_mfma_f32_32x32x16_bf16 v[184:199], v[30:33], v[204:207], v[184:199]
	s_nop 7
	s_nop 7
	ds_bpermute_b32 v225, v249, v166
	s_waitcnt lgkmcnt(0)
	v_add_f32_e32 v166, v166, v225
	v_log_f32_e32 v183, v166
	v_rcp_f32_e32 v225, v166
	s_nop 0
	v_fma_f32 v216, -v166, v225, 1.0
	v_fma_f32 v225, v225, v216, v225
	v_add_f32_e32 v183, v165, v183
	v_mul_f32_e32 v183, 0x3f317218, v183
	s_cmp_eq_u32 s1, 0
	s_cbranch_scc1 .Lband_epi_swa
	v_mov_b32_e32 v216, v225
	v_cmp_eq_u32_e32 vcc, 0, v164
	s_and_saveexec_b64 s[16:17], vcc
	global_store_dword v219, v183, s[26:27]
	s_or_b64 exec, exec, s[16:17]
	s_branch .Lband_epi_scale
.Lband_epi_swa:
	s_waitcnt lgkmcnt(0)
	v_subrev_f32_e32 v183, s30, v183
	v_mul_f32_e32 v183, 0xbfb8aa3b, v183
	v_exp_f32_e32 v183, v183
	s_nop 0
	v_add_f32_e32 v183, 1.0, v183
	v_rcp_f32_e32 v216, v183
	s_nop 0
	v_fma_f32 v217, -v183, v216, 1.0
	v_fma_f32 v216, v216, v217, v216
	v_mul_f32_e32 v216, v216, v225
.Lband_epi_scale:
	v_pk_mul_f32 v[146:147], v[146:147], v[216:217] op_sel_hi:[1,0]
	v_pk_mul_f32 v[148:149], v[148:149], v[216:217] op_sel_hi:[1,0]
	v_pk_mul_f32 v[150:151], v[150:151], v[216:217] op_sel_hi:[1,0]
	v_pk_mul_f32 v[152:153], v[152:153], v[216:217] op_sel_hi:[1,0]
	v_pk_mul_f32 v[154:155], v[154:155], v[216:217] op_sel_hi:[1,0]
	v_pk_mul_f32 v[156:157], v[156:157], v[216:217] op_sel_hi:[1,0]
	v_pk_mul_f32 v[158:159], v[158:159], v[216:217] op_sel_hi:[1,0]
	v_pk_mul_f32 v[160:161], v[160:161], v[216:217] op_sel_hi:[1,0]
	v_pk_mul_f32 v[184:185], v[184:185], v[216:217] op_sel_hi:[1,0]
	v_pk_mul_f32 v[186:187], v[186:187], v[216:217] op_sel_hi:[1,0]
	v_pk_mul_f32 v[188:189], v[188:189], v[216:217] op_sel_hi:[1,0]
	v_pk_mul_f32 v[190:191], v[190:191], v[216:217] op_sel_hi:[1,0]
	v_pk_mul_f32 v[192:193], v[192:193], v[216:217] op_sel_hi:[1,0]
	v_pk_mul_f32 v[194:195], v[194:195], v[216:217] op_sel_hi:[1,0]
	v_pk_mul_f32 v[196:197], v[196:197], v[216:217] op_sel_hi:[1,0]
	v_pk_mul_f32 v[198:199], v[198:199], v[216:217] op_sel_hi:[1,0]
	v_cvt_pk_bf16_f32 v146, v146, v147
	v_cvt_pk_bf16_f32 v147, v148, v149
	global_store_dwordx2 v218, v[146:147], s[6:7]
	v_cvt_pk_bf16_f32 v150, v150, v151
	v_cvt_pk_bf16_f32 v151, v152, v153
	global_store_dwordx2 v218, v[150:151], s[6:7] offset:16
	v_cvt_pk_bf16_f32 v154, v154, v155
	v_cvt_pk_bf16_f32 v155, v156, v157
	global_store_dwordx2 v218, v[154:155], s[6:7] offset:32
	v_cvt_pk_bf16_f32 v158, v158, v159
	v_cvt_pk_bf16_f32 v159, v160, v161
	global_store_dwordx2 v218, v[158:159], s[6:7] offset:48
	v_cvt_pk_bf16_f32 v184, v184, v185
	v_cvt_pk_bf16_f32 v185, v186, v187
	global_store_dwordx2 v218, v[184:185], s[6:7] offset:64
	v_cvt_pk_bf16_f32 v188, v188, v189
	v_cvt_pk_bf16_f32 v189, v190, v191
	global_store_dwordx2 v218, v[188:189], s[6:7] offset:80
	v_cvt_pk_bf16_f32 v192, v192, v193
	v_cvt_pk_bf16_f32 v193, v194, v195
	global_store_dwordx2 v218, v[192:193], s[6:7] offset:96
	v_cvt_pk_bf16_f32 v196, v196, v197
	v_cvt_pk_bf16_f32 v197, v198, v199
	global_store_dwordx2 v218, v[196:197], s[6:7] offset:112
	s_add_i32 s0, s0, s68
	s_cmp_lt_u32 s0, 0x4000
	s_cbranch_scc1 .Lband_item
	v_lshlrev_b32_e32 v183, 2, v220
	v_add_u32_e32 v2, 0x10000, v183
	ds_read_b32 v162, v183 offset:0
	ds_read_b32 v163, v183 offset:2048
	ds_read_b32 v164, v183 offset:4096
	ds_read_b32 v165, v183 offset:6144
	ds_read_b32 v166, v183 offset:8192
	ds_read_b32 v167, v183 offset:10240
	ds_read_b32 v168, v183 offset:12288
	ds_read_b32 v169, v183 offset:14336
	ds_read_b32 v170, v183 offset:16384
	ds_read_b32 v174, v183 offset:18432
	ds_read_b32 v175, v183 offset:20480
	ds_read_b32 v176, v183 offset:22528
	ds_read_b32 v177, v183 offset:24576
	ds_read_b32 v216, v183 offset:26624
	ds_read_b32 v217, v183 offset:28672
	ds_read_b32 v218, v183 offset:30720
	ds_read_b32 v219, v183 offset:32768
	ds_read_b32 v225, v183 offset:34816
	ds_read_b32 v227, v183 offset:36864
	ds_read_b32 v236, v183 offset:38912
	ds_read_b32 v237, v183 offset:40960
	ds_read_b32 v249, v183 offset:43008
	ds_read_b32 v200, v183 offset:45056
	ds_read_b32 v201, v183 offset:47104
	ds_read_b32 v202, v183 offset:49152
	ds_read_b32 v203, v183 offset:51200
	ds_read_b32 v204, v183 offset:53248
	ds_read_b32 v205, v183 offset:55296
	ds_read_b32 v206, v183 offset:57344
	ds_read_b32 v207, v183 offset:59392
	ds_read_b32 v208, v183 offset:61440
	ds_read_b32 v209, v183 offset:63488
	ds_read_b32 v210, v2 offset:0
	ds_read_b32 v211, v2 offset:2048
	ds_read_b32 v212, v2 offset:4096
	ds_read_b32 v213, v2 offset:6144
	ds_read_b32 v214, v2 offset:8192
	ds_read_b32 v215, v2 offset:10240
	v_lshrrev_b32_e32 v183, 6, v220
	v_lshlrev_b32_e32 v183, 7, v183
	v_add_u32_e32 v183, 0x13000, v183
	ds_read_b32 v2, v183 offset:0
	ds_read_b32 v3, v183 offset:4
	ds_read_b32 v4, v183 offset:8
	ds_read_b32 v5, v183 offset:12
	ds_read_b32 v6, v183 offset:16
	ds_read_b32 v7, v183 offset:20
	ds_read_b32 v8, v183 offset:24
	ds_read_b32 v9, v183 offset:28
	ds_read_b32 v10, v183 offset:32
	ds_read_b32 v11, v183 offset:36
	ds_read_b32 v12, v183 offset:40
	ds_read_b32 v13, v183 offset:44
	ds_read_b32 v14, v183 offset:48
	ds_read_b32 v15, v183 offset:52
	ds_read_b32 v16, v183 offset:56
	ds_read_b32 v17, v183 offset:60
	ds_read_b32 v18, v183 offset:64
	ds_read_b32 v19, v183 offset:68
	ds_read_b32 v20, v183 offset:72
	ds_read_b32 v21, v183 offset:76
	ds_read_b32 v22, v183 offset:80
	ds_read_b32 v23, v183 offset:84
	ds_read_b32 v24, v183 offset:88
	ds_read_b32 v25, v183 offset:92
	ds_read_b32 v26, v183 offset:96
	ds_read_b32 v27, v183 offset:100
	ds_read_b32 v28, v183 offset:104
	ds_read_b32 v29, v183 offset:108
	ds_read_b32 v30, v183 offset:112
	s_waitcnt lgkmcnt(0)
	v_readfirstlane_b32 s2, v2
	v_readfirstlane_b32 s3, v3
	v_readfirstlane_b32 s4, v4
	v_readfirstlane_b32 s5, v5
	v_readfirstlane_b32 s6, v6
	v_readfirstlane_b32 s7, v7
	v_readfirstlane_b32 s8, v8
	v_readfirstlane_b32 s9, v9
	v_readfirstlane_b32 s10, v10
	v_readfirstlane_b32 s11, v11
	v_readfirstlane_b32 s12, v12
	v_readfirstlane_b32 s13, v13
	v_readfirstlane_b32 s14, v14
	v_readfirstlane_b32 s15, v15
	v_readfirstlane_b32 s16, v16
	v_readfirstlane_b32 s17, v17
	v_readfirstlane_b32 s18, v18
	v_readfirstlane_b32 s19, v19
	v_readfirstlane_b32 s20, v20
	v_readfirstlane_b32 s21, v21
	v_readfirstlane_b32 s22, v22
	v_readfirstlane_b32 s23, v23
	v_readfirstlane_b32 s24, v24
	v_readfirstlane_b32 s25, v25
	v_readfirstlane_b32 s26, v26
	v_readfirstlane_b32 s27, v27
	v_readfirstlane_b32 s28, v28
	v_readfirstlane_b32 s29, v29
	v_readfirstlane_b32 s30, v30
	s_waitcnt vmcnt(0)
	s_branch .Lband_exit

.LBB0_1043:
	s_and_b64 vcc, exec, s[2:3]
	s_cbranch_vccz .LBB0_959
	v_cmp_gt_i32_e32 vcc, 16, v2
	s_and_saveexec_b64 s[2:3], vcc
	s_cbranch_execz .LBB0_958
	s_load_dwordx2 s[8:9], s[52:53], 0x98
	s_lshl_b64 s[6:7], 2, s1
	s_add_u32 s6, s6, -1
	s_addc_u32 s7, s7, -1
	v_readlane_b32 s4, v255, 36
	v_readlane_b32 s5, v255, 37
	s_waitcnt lgkmcnt(0)
	s_add_u32 s1, s8, s4
	s_addc_u32 s8, s9, s5
	s_lshl_b64 s[4:5], s[92:93], 3
	s_add_u32 s1, s1, s4
	v_readlane_b32 s4, v254, 31
	s_addc_u32 s5, s8, s5
	s_lshl_b32 s4, s4, 3
	s_add_u32 s4, s1, s4
	v_ashrrev_i32_e32 v3, 31, v2
	s_addc_u32 s5, s5, 0
	v_lshl_add_u64 v[2:3], v[2:3], 3, s[4:5]
	v_add_co_u32_e32 v2, vcc, 0x1dd00000, v2
	v_mov_b64_e32 v[4:5], s[6:7]
	s_nop 0
	v_addc_co_u32_e32 v3, vcc, 0, v3, vcc
	global_store_dwordx2 v[2:3], v[4:5], off
	s_branch .LBB0_958
.LBB0_1132:
	s_and_b64 vcc, exec, s[42:43]
	s_cbranch_vccnz .LBB0_1140
